# GLA prep item loop software-pipelined (next item's operands fetched during the current item, key loads as one address + immediates) on top of the scalar-address chain loop
# baseline (speedup 1.0000x reference)
.LBB0_985:
	s_waitcnt vmcnt(0)
	s_mov_b64 s[4:5], s[0:1]
	v_mov_b32_e32 v18, v226
	s_load_dwordx4 s[12:15], s[4:5], 0x28
	s_load_dwordx2 s[50:51], s[4:5], 0x58
	s_bfe_u32 s31, s82, 0x20005
	s_and_b32 s6, s26, 0x7c0
	v_and_b32_e32 v19, 0x7f, v18
	s_waitcnt lgkmcnt(0)
	s_add_u32 s4, s12, s86
	s_addc_u32 s5, s13, s87
	s_lshl_b32 s7, s31, 9
	s_add_u32 s4, s4, s7
	s_addc_u32 s5, s5, 0
	v_lshlrev_b32_e32 v208, 2, v19
	v_lshl_add_u64 v[0:1], s[4:5], 0, v[208:209]
	v_add_co_u32_e32 v2, vcc, s34, v0
	v_mov_b32_e32 v6, v106
	v_mov_b32_e32 v8, v108
	v_addc_co_u32_e32 v3, vcc, 0, v1, vcc
	v_add_co_u32_e32 v4, vcc, s17, v0
	s_movk_i32 s4, 0x5000
	s_nop 0
	v_addc_co_u32_e32 v5, vcc, 0, v1, vcc
	v_mov_b32_e32 v12, v112
	v_mov_b32_e32 v10, v110
	v_mov_b32_e32 v7, v107
	v_mov_b32_e32 v9, v109
	v_add_co_u32_e32 v2, vcc, s35, v0
	v_ashrrev_i32_e32 v58, 3, v18
	s_nop 0
	v_addc_co_u32_e32 v3, vcc, 0, v1, vcc
	v_add_co_u32_e32 v4, vcc, s20, v0
	v_mov_b32_e32 v25, v209
	s_nop 0
	v_addc_co_u32_e32 v5, vcc, 0, v1, vcc
	v_add_co_u32_e32 v14, vcc, s4, v0
	s_movk_i32 s4, 0x7000
	s_nop 0
	v_addc_co_u32_e32 v15, vcc, 0, v1, vcc
	v_add_co_u32_e32 v20, vcc, s21, v0
	v_mov_b32_e32 v13, v113
	v_mov_b32_e32 v11, v111
	s_nop 0
	v_mov_b32_e32 v2, v102
	s_nop 0
	v_mov_b32_e32 v4, v104
	v_addc_co_u32_e32 v21, vcc, 0, v1, vcc
	v_add_co_u32_e32 v0, vcc, s4, v0
	s_add_u32 s4, s50, 0xb400000
	s_addc_u32 s5, s51, 0
	s_and_b32 s12, s22, 0xfffff800
	s_or_b32 s12, s12, s6
	v_mov_b32_e32 v16, v116
	s_nop 0
	v_mov_b32_e32 v14, v114
	s_nop 0
	v_mov_b32_e32 v3, v103
	v_mov_b32_e32 v5, v105
	v_addc_co_u32_e32 v1, vcc, 0, v1, vcc
	s_add_u32 s6, s14, s88
	v_add_u32_e32 v20, s12, v58
	v_mov_b32_e32 v17, v117
	v_mov_b32_e32 v15, v115
	s_addc_u32 s13, s15, s89
	v_lshlrev_b32_e32 v0, 1, v18
	v_ashrrev_i32_e32 v21, 31, v20
	s_add_u32 s6, s6, s7
	v_and_b32_e32 v59, 14, v0
	v_lshlrev_b64 v[20:21], 8, v[20:21]
	s_addc_u32 s7, s13, 0
	v_lshl_add_u64 v[20:21], s[4:5], 0, v[20:21]
	v_lshlrev_b32_e32 v24, 1, v59
	v_mov_b32_e32 v22, v122
	v_lshl_add_u64 v[20:21], v[20:21], 0, v[24:25]
	s_mov_b32 s6, 0x5000000
	v_add_co_u32_e32 v20, vcc, s6, v20
	v_ashrrev_i32_e32 v1, 7, v18
	s_nop 0
	v_addc_co_u32_e32 v21, vcc, 0, v21, vcc
	v_mov_b32_e32 v60, v160
	v_lshlrev_b32_e32 v0, 4, v1
	v_add_u32_e32 v20, s12, v0
	s_lshl_b32 s6, s31, 21
	s_add_u32 s6, s4, s6
	s_addc_u32 s7, s5, 0
	v_ashrrev_i32_e32 v21, 31, v20
	v_lshlrev_b32_e32 v26, 1, v19
	v_mov_b32_e32 v27, v209
	v_lshlrev_b64 v[24:25], 8, v[20:21]
	v_lshl_add_u64 v[24:25], s[6:7], 0, v[24:25]
	v_lshl_add_u64 v[24:25], v[24:25], 0, v[26:27]
	v_add_co_u32_e32 v38, vcc, s37, v24
	s_mov_b32 s5, 0xbfb8aa3b
	s_mov_b32 s12, 0x7f800000
	v_addc_co_u32_e32 v39, vcc, 0, v25, vcc
	s_mov_b32 s4, 0x3d800000
	v_lshlrev_b32_e32 v37, 6, v58
	v_mov_b32_e32 v24, v124
	v_mov_b32_e32 v23, v123
	v_mov_b32_e32 v25, v125
	v_mov_b32_e32 v26, v126
	v_mov_b32_e32 v27, v127
	v_mov_b32_e32 v28, v128
	v_mov_b32_e32 v29, v129
	v_mov_b32_e32 v30, v130
	v_mov_b32_e32 v31, v131
	v_mov_b32_e32 v32, v132
	v_mov_b32_e32 v33, v133
	v_mov_b32_e32 v34, v134
	v_mov_b32_e32 v35, v135
	v_mov_b32_e32 v36, v136
	v_mov_b32_e32 v20, v120
	v_mov_b32_e32 v21, v121
	s_branch .Lprep_body
.Lprep_first:
	s_mov_b64 s[4:5], s[0:1]
	v_mov_b32_e32 v18, v226
	s_load_dwordx4 s[12:15], s[4:5], 0x28
	s_load_dwordx2 s[50:51], s[4:5], 0x58
	s_bfe_u32 s31, s82, 0x20005
	s_and_b32 s6, s26, 0x7c0
	v_and_b32_e32 v19, 0x7f, v18
	s_waitcnt lgkmcnt(0)
	s_add_u32 s4, s12, s86
	s_addc_u32 s5, s13, s87
	s_lshl_b32 s7, s31, 9
	s_add_u32 s4, s4, s7
	s_addc_u32 s5, s5, 0
	v_lshlrev_b32_e32 v208, 2, v19
	v_lshl_add_u64 v[0:1], s[4:5], 0, v[208:209]
	v_add_co_u32_e32 v2, vcc, s34, v0
	global_load_dword v6, v208, s[4:5]
	global_load_dword v8, v208, s[4:5] offset:2048
	v_addc_co_u32_e32 v3, vcc, 0, v1, vcc
	v_add_co_u32_e32 v4, vcc, s17, v0
	s_movk_i32 s4, 0x5000
	s_nop 0
	v_addc_co_u32_e32 v5, vcc, 0, v1, vcc
	global_load_dword v12, v[4:5], off offset:-4096
	global_load_dword v10, v[2:3], off offset:2048
	global_load_dword v7, v[4:5], off
	global_load_dword v9, v[4:5], off offset:2048
	v_add_co_u32_e32 v2, vcc, s35, v0
	v_ashrrev_i32_e32 v58, 3, v18
	s_nop 0
	v_addc_co_u32_e32 v3, vcc, 0, v1, vcc
	v_add_co_u32_e32 v4, vcc, s20, v0
	v_mov_b32_e32 v25, v209
	s_nop 0
	v_addc_co_u32_e32 v5, vcc, 0, v1, vcc
	v_add_co_u32_e32 v14, vcc, s4, v0
	s_movk_i32 s4, 0x7000
	s_nop 0
	v_addc_co_u32_e32 v15, vcc, 0, v1, vcc
	v_add_co_u32_e32 v20, vcc, s21, v0
	global_load_dword v13, v[4:5], off offset:-4096
	global_load_dword v11, v[2:3], off offset:2048
	s_nop 0
	global_load_dword v2, v[4:5], off
	s_nop 0
	global_load_dword v4, v[4:5], off offset:2048
	v_addc_co_u32_e32 v21, vcc, 0, v1, vcc
	v_add_co_u32_e32 v0, vcc, s4, v0
	s_add_u32 s4, s50, 0xb400000
	s_addc_u32 s5, s51, 0
	s_and_b32 s12, s22, 0xfffff800
	s_or_b32 s12, s12, s6
	global_load_dword v16, v[20:21], off offset:-4096
	s_nop 0
	global_load_dword v14, v[14:15], off offset:2048
	s_nop 0
	global_load_dword v3, v[20:21], off
	global_load_dword v5, v[20:21], off offset:2048
	v_addc_co_u32_e32 v1, vcc, 0, v1, vcc
	s_add_u32 s6, s14, s88
	v_add_u32_e32 v20, s12, v58
	global_load_dword v17, v[0:1], off
	global_load_dword v15, v[0:1], off offset:2048
	s_addc_u32 s13, s15, s89
	v_lshlrev_b32_e32 v0, 1, v18
	v_ashrrev_i32_e32 v21, 31, v20
	s_add_u32 s6, s6, s7
	v_and_b32_e32 v59, 14, v0
	v_lshlrev_b64 v[20:21], 8, v[20:21]
	s_addc_u32 s7, s13, 0
	v_lshl_add_u64 v[20:21], s[4:5], 0, v[20:21]
	v_lshlrev_b32_e32 v24, 1, v59
	global_load_dword v22, v208, s[6:7]
	v_lshl_add_u64 v[20:21], v[20:21], 0, v[24:25]
	s_mov_b32 s6, 0x5000000
	v_add_co_u32_e32 v20, vcc, s6, v20
	v_ashrrev_i32_e32 v1, 7, v18
	s_nop 0
	v_addc_co_u32_e32 v21, vcc, 0, v21, vcc
	global_load_dword v60, v[20:21], off
	v_lshlrev_b32_e32 v0, 4, v1
	v_add_u32_e32 v20, s12, v0
	s_lshl_b32 s6, s31, 21
	s_add_u32 s6, s4, s6
	s_addc_u32 s7, s5, 0
	v_ashrrev_i32_e32 v21, 31, v20
	v_lshlrev_b32_e32 v26, 1, v19
	v_mov_b32_e32 v27, v209
	v_lshlrev_b64 v[24:25], 8, v[20:21]
	v_lshl_add_u64 v[24:25], s[6:7], 0, v[24:25]
	v_lshl_add_u64 v[24:25], v[24:25], 0, v[26:27]
	v_add_co_u32_e32 v38, vcc, s37, v24
	s_mov_b32 s5, 0xbfb8aa3b
	s_mov_b32 s12, 0x7f800000
	v_addc_co_u32_e32 v39, vcc, 0, v25, vcc
	s_mov_b32 s4, 0x3d800000
	v_lshlrev_b32_e32 v37, 6, v58
	global_load_ushort v24, v[38:39], off
	global_load_ushort v23, v[38:39], off offset:256
	global_load_ushort v25, v[38:39], off offset:512
	global_load_ushort v26, v[38:39], off offset:768
	global_load_ushort v27, v[38:39], off offset:1024
	global_load_ushort v28, v[38:39], off offset:1280
	global_load_ushort v29, v[38:39], off offset:1536
	global_load_ushort v30, v[38:39], off offset:1792
	global_load_ushort v31, v[38:39], off offset:2048
	global_load_ushort v32, v[38:39], off offset:2304
	global_load_ushort v33, v[38:39], off offset:2560
	global_load_ushort v34, v[38:39], off offset:2816
	global_load_ushort v35, v[38:39], off offset:3072
	global_load_ushort v36, v[38:39], off offset:3328
	global_load_ushort v20, v[38:39], off offset:3584
	global_load_ushort v21, v[38:39], off offset:3840
.Lprep_body:
	v_lshlrev_b32_e32 v39, 2, v59
	s_waitcnt vmcnt(0)
	v_lshlrev_b32_e32 v38, 16, v60
	v_add3_u32 v37, 0, v37, v39
	v_and_b32_e32 v39, 0xffff0000, v60
	s_barrier
	ds_write_b64 v37, v[38:39]
	v_lshl_add_u32 v38, v1, 10, 0
	s_waitcnt lgkmcnt(0)
	s_barrier
	ds_read_b128 v[40:43], v38
	ds_read_b128 v[44:47], v38 offset:16
	ds_read_b128 v[48:51], v38 offset:32
	ds_read_b128 v[52:55], v38 offset:48
	s_add_i32 s32, s82, s84
	s_cmpk_gt_i32 s32, 0x1ff
	s_cbranch_scc1 .Lprep_nopf
	s_load_dwordx4 s[40:43], s[0:1], 0x28
	s_bfe_u32 s32, s32, 0x20005
	s_lshl_b32 s57, s32, 9
	s_add_i32 s56, s26, s30
	s_and_b32 s56, s56, 0x7c0
	s_add_i32 s45, s22, s23
	s_and_b32 s45, s45, 0xfffff800
	s_or_b32 s45, s45, s56
	v_and_b32_e32 v100, 0x7f, v226
	v_lshlrev_b32_e32 v164, 2, v100
	v_add_u32_e32 v166, 0x1000, v164
	v_add_u32_e32 v167, 0x3000, v164
	v_add_u32_e32 v168, 0x5000, v164
	v_add_u32_e32 v169, 0x7000, v164
	s_waitcnt lgkmcnt(0)
	s_add_u32 s40, s40, s86
	s_addc_u32 s41, s41, s87
	s_add_u32 s40, s40, s57
	s_addc_u32 s41, s41, 0
	s_add_u32 s42, s42, s88
	s_addc_u32 s43, s43, s89
	s_add_u32 s42, s42, s57
	s_addc_u32 s43, s43, 0
	global_load_dword v106, v166, s[40:41] offset:-4096
	global_load_dword v108, v166, s[40:41] offset:-2048
	global_load_dword v112, v166, s[40:41]
	global_load_dword v110, v166, s[40:41] offset:2048
	global_load_dword v107, v167, s[40:41] offset:-4096
	global_load_dword v109, v167, s[40:41] offset:-2048
	global_load_dword v113, v167, s[40:41]
	global_load_dword v111, v167, s[40:41] offset:2048
	global_load_dword v102, v168, s[40:41] offset:-4096
	global_load_dword v104, v168, s[40:41] offset:-2048
	global_load_dword v116, v168, s[40:41]
	global_load_dword v114, v168, s[40:41] offset:2048
	global_load_dword v103, v169, s[40:41] offset:-4096
	global_load_dword v105, v169, s[40:41] offset:-2048
	global_load_dword v117, v169, s[40:41]
	global_load_dword v115, v169, s[40:41] offset:2048
	global_load_dword v122, v164, s[42:43]
	s_add_u32 s56, s50, 0xb400000
	s_addc_u32 s57, s51, 0
	v_lshrrev_b32_e32 v170, 3, v226
	v_add_u32_e32 v170, s45, v170
	v_lshlrev_b32_e32 v170, 8, v170
	v_and_b32_e32 v171, 7, v226
	v_lshl_add_u32 v170, v171, 2, v170
	v_add_u32_e32 v170, 0x5000000, v170
	global_load_dword v160, v170, s[56:57]
	v_lshrrev_b32_e32 v171, 7, v226
	v_lshl_add_u32 v171, v171, 4, s45
	v_lshlrev_b32_e32 v171, 8, v171
	v_lshl_add_u32 v171, v100, 1, v171
	s_lshl_b32 s32, s32, 21
	s_add_i32 s32, s32, 0x800000
	v_add_u32_e32 v171, s32, v171
	global_load_ushort v124, v171, s[56:57]
	global_load_ushort v123, v171, s[56:57] offset:256
	global_load_ushort v125, v171, s[56:57] offset:512
	global_load_ushort v126, v171, s[56:57] offset:768
	global_load_ushort v127, v171, s[56:57] offset:1024
	global_load_ushort v128, v171, s[56:57] offset:1280
	global_load_ushort v129, v171, s[56:57] offset:1536
	global_load_ushort v130, v171, s[56:57] offset:1792
	global_load_ushort v131, v171, s[56:57] offset:2048
	global_load_ushort v132, v171, s[56:57] offset:2304
	global_load_ushort v133, v171, s[56:57] offset:2560
	global_load_ushort v134, v171, s[56:57] offset:2816
	global_load_ushort v135, v171, s[56:57] offset:3072
	global_load_ushort v136, v171, s[56:57] offset:3328
	global_load_ushort v120, v171, s[56:57] offset:3584
	global_load_ushort v121, v171, s[56:57] offset:3840
.Lprep_nopf:
	s_waitcnt lgkmcnt(3)
	v_mov_b32_e32 v56, v40
	s_waitcnt lgkmcnt(2)
	v_mov_b32_e32 v57, v44
	v_mov_b32_e32 v44, v41
	v_pk_mul_f32 v[40:41], v[8:9], v[44:45]
	v_mov_b32_e32 v44, v42
	v_pk_fma_f32 v[40:41], v[6:7], v[56:57], v[40:41]
	v_mov_b32_e32 v45, v46
	v_pk_fma_f32 v[40:41], v[12:13], v[44:45], v[40:41]
	v_mov_b32_e32 v46, v43
	v_pk_fma_f32 v[40:41], v[10:11], v[46:47], v[40:41]
	s_nop 0
	v_add_f32_e32 v37, v22, v40
	v_add_f32_e32 v37, v37, v41
	s_waitcnt lgkmcnt(0)
	v_mov_b32_e32 v41, v52
	v_mov_b32_e32 v52, v49
	v_mov_b32_e32 v40, v48
	v_pk_mul_f32 v[42:43], v[4:5], v[52:53]
	s_nop 0
	v_pk_fma_f32 v[40:41], v[2:3], v[40:41], v[42:43]
	v_mov_b32_e32 v42, v50
	v_mov_b32_e32 v43, v54
	v_pk_fma_f32 v[40:41], v[16:17], v[42:43], v[40:41]
	v_mov_b32_e32 v54, v51
	v_pk_fma_f32 v[40:41], v[14:15], v[54:55], v[40:41]
	s_nop 0
	v_add_f32_e32 v37, v37, v40
	v_add_f32_e32 v37, v37, v41
	v_min_f32_e32 v39, 0, v37
	v_mul_f32_e64 v37, |v37|, s5
	v_exp_f32_e32 v37, v37
	s_nop 0
	v_add_f32_e32 v37, 1.0, v37
	v_cmp_gt_f32_e32 vcc, s37, v37
	s_nop 1
	v_cndmask_b32_e64 v40, 0, 32, vcc
	v_ldexp_f32 v37, v37, v40
	v_log_f32_e32 v37, v37
	s_nop 0
	v_mul_f32_e32 v40, 0x3f317217, v37
	v_fma_f32 v40, v37, s2, -v40
	v_fmac_f32_e32 v40, 0x3377d1cf, v37
	v_fmac_f32_e32 v40, 0x3f317217, v37
	v_cmp_lt_f32_e64 s[6:7], |v37|, s12
	s_nop 1
	v_cndmask_b32_e64 v37, v37, v40, s[6:7]
	v_cndmask_b32_e32 v40, 0, v232, vcc
	v_sub_f32_e32 v37, v37, v40
	ds_read_b128 v[40:43], v38 offset:64
	ds_read_b128 v[44:47], v38 offset:80
	v_sub_f32_e32 v37, v39, v37
	v_fma_f32 v37, v37, s4, 0
	s_movk_i32 s4, 0x80
	s_waitcnt lgkmcnt(1)
	v_mov_b32_e32 v48, v40
	s_waitcnt lgkmcnt(0)
	v_mov_b32_e32 v49, v44
	v_mov_b32_e32 v44, v41
	v_pk_mul_f32 v[40:41], v[8:9], v[44:45]
	v_mov_b32_e32 v44, v42
	v_pk_fma_f32 v[40:41], v[6:7], v[48:49], v[40:41]
	v_mov_b32_e32 v45, v46
	v_pk_fma_f32 v[40:41], v[12:13], v[44:45], v[40:41]
	v_mov_b32_e32 v46, v43
	v_pk_fma_f32 v[40:41], v[10:11], v[46:47], v[40:41]
	s_nop 0
	v_add_f32_e32 v39, v22, v40
	v_add_f32_e32 v39, v39, v41
	ds_read_b128 v[40:43], v38 offset:96
	ds_read_b128 v[44:47], v38 offset:112
	s_waitcnt lgkmcnt(1)
	v_mov_b32_e32 v48, v40
	s_waitcnt lgkmcnt(0)
	v_mov_b32_e32 v49, v44
	v_mov_b32_e32 v44, v41
	v_pk_mul_f32 v[40:41], v[4:5], v[44:45]
	v_mov_b32_e32 v44, v42
	v_pk_fma_f32 v[40:41], v[2:3], v[48:49], v[40:41]
	v_mov_b32_e32 v45, v46
	v_pk_fma_f32 v[40:41], v[16:17], v[44:45], v[40:41]
	v_mov_b32_e32 v46, v43
	v_pk_fma_f32 v[40:41], v[14:15], v[46:47], v[40:41]
	s_nop 0
	v_add_f32_e32 v39, v39, v40
	v_add_f32_e32 v39, v39, v41
	v_min_f32_e32 v40, 0, v39
	v_mul_f32_e64 v39, |v39|, s5
	v_exp_f32_e32 v39, v39
	s_nop 0
	v_add_f32_e32 v39, 1.0, v39
	v_cmp_gt_f32_e32 vcc, s37, v39
	s_nop 1
	v_cndmask_b32_e64 v41, 0, 32, vcc
	v_ldexp_f32 v39, v39, v41
	v_log_f32_e32 v39, v39
	s_nop 0
	v_mul_f32_e32 v41, 0x3f317217, v39
	v_fma_f32 v41, v39, s2, -v41
	v_fmac_f32_e32 v41, 0x3377d1cf, v39
	v_fmac_f32_e32 v41, 0x3f317217, v39
	v_cmp_lt_f32_e64 s[6:7], |v39|, s12
	s_nop 1
	v_cndmask_b32_e64 v39, v39, v41, s[6:7]
	v_cndmask_b32_e32 v41, 0, v232, vcc
	v_sub_f32_e32 v39, v39, v41
	v_sub_f32_e32 v39, v40, v39
	ds_read_b128 v[40:43], v38 offset:128
	ds_read_b128 v[44:47], v38 offset:144
	v_fmamk_f32 v39, v39, 0x3d800000, v37
	s_waitcnt lgkmcnt(1)
	v_mov_b32_e32 v48, v40
	s_waitcnt lgkmcnt(0)
	v_mov_b32_e32 v49, v44
	v_mov_b32_e32 v44, v41
	v_pk_mul_f32 v[40:41], v[8:9], v[44:45]
	v_mov_b32_e32 v44, v42
	v_pk_fma_f32 v[40:41], v[6:7], v[48:49], v[40:41]
	v_mov_b32_e32 v45, v46
	v_pk_fma_f32 v[40:41], v[12:13], v[44:45], v[40:41]
	v_mov_b32_e32 v46, v43
	v_pk_fma_f32 v[40:41], v[10:11], v[46:47], v[40:41]
	s_nop 0
	v_add_f32_e32 v40, v22, v40
	v_add_f32_e32 v50, v40, v41
	ds_read_b128 v[40:43], v38 offset:160
	ds_read_b128 v[44:47], v38 offset:176
	s_waitcnt lgkmcnt(1)
	v_mov_b32_e32 v48, v40
	s_waitcnt lgkmcnt(0)
	v_mov_b32_e32 v49, v44
	v_mov_b32_e32 v44, v41
	v_pk_mul_f32 v[40:41], v[4:5], v[44:45]
	v_mov_b32_e32 v44, v42
	v_pk_fma_f32 v[40:41], v[2:3], v[48:49], v[40:41]
	v_mov_b32_e32 v45, v46
	v_pk_fma_f32 v[40:41], v[16:17], v[44:45], v[40:41]
	v_mov_b32_e32 v46, v43
	v_pk_fma_f32 v[40:41], v[14:15], v[46:47], v[40:41]
	s_nop 0
	v_add_f32_e32 v40, v50, v40
	v_add_f32_e32 v40, v40, v41
	v_min_f32_e32 v41, 0, v40
	v_mul_f32_e64 v40, |v40|, s5
	v_exp_f32_e32 v40, v40
	s_nop 0
	v_add_f32_e32 v40, 1.0, v40
	v_cmp_gt_f32_e32 vcc, s37, v40
	s_nop 1
	v_cndmask_b32_e64 v42, 0, 32, vcc
	v_ldexp_f32 v40, v40, v42
	v_log_f32_e32 v40, v40
	s_nop 0
	v_mul_f32_e32 v42, 0x3f317217, v40
	v_fma_f32 v42, v40, s2, -v42
	v_fmac_f32_e32 v42, 0x3377d1cf, v40
	v_fmac_f32_e32 v42, 0x3f317217, v40
	v_cmp_lt_f32_e64 s[6:7], |v40|, s12
	s_nop 1
	v_cndmask_b32_e64 v40, v40, v42, s[6:7]
	v_cndmask_b32_e32 v42, 0, v232, vcc
	v_sub_f32_e32 v40, v40, v42
	ds_read_b128 v[42:45], v38 offset:192
	ds_read_b128 v[46:49], v38 offset:208
	v_sub_f32_e32 v40, v41, v40
	v_fmamk_f32 v40, v40, 0x3d800000, v39
	s_waitcnt lgkmcnt(1)
	v_mov_b32_e32 v50, v42
	s_waitcnt lgkmcnt(0)
	v_mov_b32_e32 v51, v46
	v_mov_b32_e32 v46, v43
	v_pk_mul_f32 v[42:43], v[8:9], v[46:47]
	v_mov_b32_e32 v46, v44
	v_pk_fma_f32 v[42:43], v[6:7], v[50:51], v[42:43]
	v_mov_b32_e32 v47, v48
	v_pk_fma_f32 v[42:43], v[12:13], v[46:47], v[42:43]
	v_mov_b32_e32 v48, v45
	v_pk_fma_f32 v[42:43], v[10:11], v[48:49], v[42:43]
	s_nop 0
	v_add_f32_e32 v41, v22, v42
	v_add_f32_e32 v41, v41, v43
	ds_read_b128 v[42:45], v38 offset:224
	ds_read_b128 v[46:49], v38 offset:240
	s_waitcnt lgkmcnt(1)
	v_mov_b32_e32 v50, v42
	s_waitcnt lgkmcnt(0)
	v_mov_b32_e32 v51, v46
	v_mov_b32_e32 v46, v43
	v_pk_mul_f32 v[42:43], v[4:5], v[46:47]
	v_mov_b32_e32 v46, v44
	v_pk_fma_f32 v[42:43], v[2:3], v[50:51], v[42:43]
	v_mov_b32_e32 v47, v48
	v_pk_fma_f32 v[42:43], v[16:17], v[46:47], v[42:43]
	v_mov_b32_e32 v48, v45
	v_pk_fma_f32 v[42:43], v[14:15], v[48:49], v[42:43]
	s_nop 0
	v_add_f32_e32 v41, v41, v42
	v_add_f32_e32 v41, v41, v43
	v_min_f32_e32 v42, 0, v41
	v_mul_f32_e64 v41, |v41|, s5
	v_exp_f32_e32 v41, v41
	s_nop 0
	v_add_f32_e32 v41, 1.0, v41
	v_cmp_gt_f32_e32 vcc, s37, v41
	s_nop 1
	v_cndmask_b32_e64 v43, 0, 32, vcc
	v_ldexp_f32 v41, v41, v43
	v_log_f32_e32 v41, v41
	s_nop 0
	v_mul_f32_e32 v43, 0x3f317217, v41
	v_fma_f32 v43, v41, s2, -v43
	v_fmac_f32_e32 v43, 0x3377d1cf, v41
	v_fmac_f32_e32 v43, 0x3f317217, v41
	v_cmp_lt_f32_e64 s[6:7], |v41|, s12
	s_nop 1
	v_cndmask_b32_e64 v41, v41, v43, s[6:7]
	v_cndmask_b32_e32 v43, 0, v232, vcc
	v_sub_f32_e32 v41, v41, v43
	v_sub_f32_e32 v41, v42, v41
	ds_read_b128 v[42:45], v38 offset:256
	ds_read_b128 v[46:49], v38 offset:272
	v_fmamk_f32 v41, v41, 0x3d800000, v40
	s_waitcnt lgkmcnt(1)
	v_mov_b32_e32 v50, v42
	s_waitcnt lgkmcnt(0)
	v_mov_b32_e32 v51, v46
	v_mov_b32_e32 v46, v43
	v_pk_mul_f32 v[42:43], v[8:9], v[46:47]
	v_mov_b32_e32 v46, v44
	v_pk_fma_f32 v[42:43], v[6:7], v[50:51], v[42:43]
	v_mov_b32_e32 v47, v48
	v_pk_fma_f32 v[42:43], v[12:13], v[46:47], v[42:43]
	v_mov_b32_e32 v48, v45
	v_pk_fma_f32 v[42:43], v[10:11], v[48:49], v[42:43]
	s_nop 0
	v_add_f32_e32 v42, v22, v42
	v_add_f32_e32 v52, v42, v43
	ds_read_b128 v[42:45], v38 offset:288
	ds_read_b128 v[46:49], v38 offset:304
	s_waitcnt lgkmcnt(1)
	v_mov_b32_e32 v50, v42
	s_waitcnt lgkmcnt(0)
	v_mov_b32_e32 v51, v46
	v_mov_b32_e32 v46, v43
	v_pk_mul_f32 v[42:43], v[4:5], v[46:47]
	v_mov_b32_e32 v46, v44
	v_pk_fma_f32 v[42:43], v[2:3], v[50:51], v[42:43]
	v_mov_b32_e32 v47, v48
	v_pk_fma_f32 v[42:43], v[16:17], v[46:47], v[42:43]
	v_mov_b32_e32 v48, v45
	v_pk_fma_f32 v[42:43], v[14:15], v[48:49], v[42:43]
	s_nop 0
	v_add_f32_e32 v42, v52, v42
	v_add_f32_e32 v42, v42, v43
	v_min_f32_e32 v43, 0, v42
	v_mul_f32_e64 v42, |v42|, s5
	v_exp_f32_e32 v42, v42
	s_nop 0
	v_add_f32_e32 v42, 1.0, v42
	v_cmp_gt_f32_e32 vcc, s37, v42
	s_nop 1
	v_cndmask_b32_e64 v44, 0, 32, vcc
	v_ldexp_f32 v42, v42, v44
	v_log_f32_e32 v42, v42
	s_nop 0
	v_mul_f32_e32 v44, 0x3f317217, v42
	v_fma_f32 v44, v42, s2, -v44
	v_fmac_f32_e32 v44, 0x3377d1cf, v42
	v_fmac_f32_e32 v44, 0x3f317217, v42
	v_cmp_lt_f32_e64 s[6:7], |v42|, s12
	s_nop 1
	v_cndmask_b32_e64 v42, v42, v44, s[6:7]
	v_cndmask_b32_e32 v44, 0, v232, vcc
	v_sub_f32_e32 v42, v42, v44
	ds_read_b128 v[44:47], v38 offset:320
	ds_read_b128 v[48:51], v38 offset:336
	v_sub_f32_e32 v42, v43, v42
	v_fmamk_f32 v42, v42, 0x3d800000, v41
	s_waitcnt lgkmcnt(1)
	v_mov_b32_e32 v52, v44
	s_waitcnt lgkmcnt(0)
	v_mov_b32_e32 v53, v48
	v_mov_b32_e32 v48, v45
	v_pk_mul_f32 v[44:45], v[8:9], v[48:49]
	v_mov_b32_e32 v48, v46
	v_pk_fma_f32 v[44:45], v[6:7], v[52:53], v[44:45]
	v_mov_b32_e32 v49, v50
	v_pk_fma_f32 v[44:45], v[12:13], v[48:49], v[44:45]
	v_mov_b32_e32 v50, v47
	v_pk_fma_f32 v[44:45], v[10:11], v[50:51], v[44:45]
	s_nop 0
	v_add_f32_e32 v43, v22, v44
	v_add_f32_e32 v43, v43, v45
	ds_read_b128 v[44:47], v38 offset:352
	ds_read_b128 v[48:51], v38 offset:368
	s_waitcnt lgkmcnt(1)
	v_mov_b32_e32 v52, v44
	s_waitcnt lgkmcnt(0)
	v_mov_b32_e32 v53, v48
	v_mov_b32_e32 v48, v45
	v_pk_mul_f32 v[44:45], v[4:5], v[48:49]
	v_mov_b32_e32 v48, v46
	v_pk_fma_f32 v[44:45], v[2:3], v[52:53], v[44:45]
	v_mov_b32_e32 v49, v50
	v_pk_fma_f32 v[44:45], v[16:17], v[48:49], v[44:45]
	v_mov_b32_e32 v50, v47
	v_pk_fma_f32 v[44:45], v[14:15], v[50:51], v[44:45]
	s_nop 0
	v_add_f32_e32 v43, v43, v44
	v_add_f32_e32 v43, v43, v45
	v_min_f32_e32 v44, 0, v43
	v_mul_f32_e64 v43, |v43|, s5
	v_exp_f32_e32 v43, v43
	s_nop 0
	v_add_f32_e32 v43, 1.0, v43
	v_cmp_gt_f32_e32 vcc, s37, v43
	s_nop 1
	v_cndmask_b32_e64 v45, 0, 32, vcc
	v_ldexp_f32 v43, v43, v45
	v_log_f32_e32 v43, v43
	s_nop 0
	v_mul_f32_e32 v45, 0x3f317217, v43
	v_fma_f32 v45, v43, s2, -v45
	v_fmac_f32_e32 v45, 0x3377d1cf, v43
	v_fmac_f32_e32 v45, 0x3f317217, v43
	v_cmp_lt_f32_e64 s[6:7], |v43|, s12
	s_nop 1
	v_cndmask_b32_e64 v43, v43, v45, s[6:7]
	v_cndmask_b32_e32 v45, 0, v232, vcc
	v_sub_f32_e32 v43, v43, v45
	v_sub_f32_e32 v43, v44, v43
	ds_read_b128 v[44:47], v38 offset:384
	ds_read_b128 v[48:51], v38 offset:400
	v_fmamk_f32 v43, v43, 0x3d800000, v42
	s_waitcnt lgkmcnt(1)
	v_mov_b32_e32 v52, v44
	s_waitcnt lgkmcnt(0)
	v_mov_b32_e32 v53, v48
	v_mov_b32_e32 v48, v45
	v_pk_mul_f32 v[44:45], v[8:9], v[48:49]
	v_mov_b32_e32 v48, v46
	v_pk_fma_f32 v[44:45], v[6:7], v[52:53], v[44:45]
	v_mov_b32_e32 v49, v50
	v_pk_fma_f32 v[44:45], v[12:13], v[48:49], v[44:45]
	v_mov_b32_e32 v50, v47
	v_pk_fma_f32 v[44:45], v[10:11], v[50:51], v[44:45]
	s_nop 0
	v_add_f32_e32 v44, v22, v44
	v_add_f32_e32 v54, v44, v45
	ds_read_b128 v[44:47], v38 offset:416
	ds_read_b128 v[48:51], v38 offset:432
	s_waitcnt lgkmcnt(1)
	v_mov_b32_e32 v52, v44
	s_waitcnt lgkmcnt(0)
	v_mov_b32_e32 v53, v48
	v_mov_b32_e32 v48, v45
	v_pk_mul_f32 v[44:45], v[4:5], v[48:49]
	v_mov_b32_e32 v48, v46
	v_pk_fma_f32 v[44:45], v[2:3], v[52:53], v[44:45]
	v_mov_b32_e32 v49, v50
	v_pk_fma_f32 v[44:45], v[16:17], v[48:49], v[44:45]
	v_mov_b32_e32 v50, v47
	v_pk_fma_f32 v[44:45], v[14:15], v[50:51], v[44:45]
	s_nop 0
	v_add_f32_e32 v44, v54, v44
	v_add_f32_e32 v44, v44, v45
	v_min_f32_e32 v45, 0, v44
	v_mul_f32_e64 v44, |v44|, s5
	v_exp_f32_e32 v44, v44
	s_nop 0
	v_add_f32_e32 v44, 1.0, v44
	v_cmp_gt_f32_e32 vcc, s37, v44
	s_nop 1
	v_cndmask_b32_e64 v46, 0, 32, vcc
	v_ldexp_f32 v44, v44, v46
	v_log_f32_e32 v44, v44
	s_nop 0
	v_mul_f32_e32 v46, 0x3f317217, v44
	v_fma_f32 v46, v44, s2, -v46
	v_fmac_f32_e32 v46, 0x3377d1cf, v44
	v_fmac_f32_e32 v46, 0x3f317217, v44
	v_cmp_lt_f32_e64 s[6:7], |v44|, s12
	s_nop 1
	v_cndmask_b32_e64 v44, v44, v46, s[6:7]
	v_cndmask_b32_e32 v46, 0, v232, vcc
	v_sub_f32_e32 v44, v44, v46
	ds_read_b128 v[46:49], v38 offset:448
	ds_read_b128 v[50:53], v38 offset:464
	v_sub_f32_e32 v44, v45, v44
	v_fmamk_f32 v44, v44, 0x3d800000, v43
	s_waitcnt lgkmcnt(1)
	v_mov_b32_e32 v54, v46
	s_waitcnt lgkmcnt(0)
	v_mov_b32_e32 v55, v50
	v_mov_b32_e32 v50, v47
	v_pk_mul_f32 v[46:47], v[8:9], v[50:51]
	v_mov_b32_e32 v50, v48
	v_pk_fma_f32 v[46:47], v[6:7], v[54:55], v[46:47]
	v_mov_b32_e32 v51, v52
	v_pk_fma_f32 v[46:47], v[12:13], v[50:51], v[46:47]
	v_mov_b32_e32 v52, v49
	v_pk_fma_f32 v[46:47], v[10:11], v[52:53], v[46:47]
	s_nop 0
	v_add_f32_e32 v45, v22, v46
	v_add_f32_e32 v45, v45, v47
	ds_read_b128 v[46:49], v38 offset:480
	ds_read_b128 v[50:53], v38 offset:496
	s_waitcnt lgkmcnt(1)
	v_mov_b32_e32 v54, v46
	s_waitcnt lgkmcnt(0)
	v_mov_b32_e32 v55, v50
	v_mov_b32_e32 v50, v47
	v_pk_mul_f32 v[46:47], v[4:5], v[50:51]
	v_mov_b32_e32 v50, v48
	v_pk_fma_f32 v[46:47], v[2:3], v[54:55], v[46:47]
	v_mov_b32_e32 v51, v52
	v_pk_fma_f32 v[46:47], v[16:17], v[50:51], v[46:47]
	v_mov_b32_e32 v52, v49
	v_pk_fma_f32 v[46:47], v[14:15], v[52:53], v[46:47]
	s_nop 0
	v_add_f32_e32 v45, v45, v46
	v_add_f32_e32 v45, v45, v47
	v_min_f32_e32 v46, 0, v45
	v_mul_f32_e64 v45, |v45|, s5
	v_exp_f32_e32 v45, v45
	s_nop 0
	v_add_f32_e32 v45, 1.0, v45
	v_cmp_gt_f32_e32 vcc, s37, v45
	s_nop 1
	v_cndmask_b32_e64 v47, 0, 32, vcc
	v_ldexp_f32 v45, v45, v47
	v_log_f32_e32 v45, v45
	s_nop 0
	v_mul_f32_e32 v47, 0x3f317217, v45
	v_fma_f32 v47, v45, s2, -v47
	v_fmac_f32_e32 v47, 0x3377d1cf, v45
	v_fmac_f32_e32 v47, 0x3f317217, v45
	v_cmp_lt_f32_e64 s[6:7], |v45|, s12
	s_nop 1
	v_cndmask_b32_e64 v45, v45, v47, s[6:7]
	v_cndmask_b32_e32 v47, 0, v232, vcc
	v_sub_f32_e32 v45, v45, v47
	v_sub_f32_e32 v45, v46, v45
	ds_read_b128 v[46:49], v38 offset:512
	ds_read_b128 v[50:53], v38 offset:528
	v_fmamk_f32 v45, v45, 0x3d800000, v44
	s_waitcnt lgkmcnt(1)
	v_mov_b32_e32 v54, v46
	s_waitcnt lgkmcnt(0)
	v_mov_b32_e32 v55, v50
	v_mov_b32_e32 v50, v47
	v_pk_mul_f32 v[46:47], v[8:9], v[50:51]
	v_mov_b32_e32 v50, v48
	v_pk_fma_f32 v[46:47], v[6:7], v[54:55], v[46:47]
	v_mov_b32_e32 v51, v52
	v_pk_fma_f32 v[46:47], v[12:13], v[50:51], v[46:47]
	v_mov_b32_e32 v52, v49
	v_pk_fma_f32 v[46:47], v[10:11], v[52:53], v[46:47]
	s_nop 0
	v_add_f32_e32 v46, v22, v46
	v_add_f32_e32 v56, v46, v47
	ds_read_b128 v[46:49], v38 offset:544
	ds_read_b128 v[50:53], v38 offset:560
	s_waitcnt lgkmcnt(1)
	v_mov_b32_e32 v54, v46
	s_waitcnt lgkmcnt(0)
	v_mov_b32_e32 v55, v50
	v_mov_b32_e32 v50, v47
	v_pk_mul_f32 v[46:47], v[4:5], v[50:51]
	v_mov_b32_e32 v50, v48
	v_pk_fma_f32 v[46:47], v[2:3], v[54:55], v[46:47]
	v_mov_b32_e32 v51, v52
	v_pk_fma_f32 v[46:47], v[16:17], v[50:51], v[46:47]
	v_mov_b32_e32 v52, v49
	v_pk_fma_f32 v[46:47], v[14:15], v[52:53], v[46:47]
	s_nop 0
	v_add_f32_e32 v46, v56, v46
	v_add_f32_e32 v46, v46, v47
	v_min_f32_e32 v47, 0, v46
	v_mul_f32_e64 v46, |v46|, s5
	v_exp_f32_e32 v46, v46
	s_nop 0
	v_add_f32_e32 v46, 1.0, v46
	v_cmp_gt_f32_e32 vcc, s37, v46
	s_nop 1
	v_cndmask_b32_e64 v48, 0, 32, vcc
	v_ldexp_f32 v46, v46, v48
	v_log_f32_e32 v46, v46
	s_nop 0
	v_mul_f32_e32 v48, 0x3f317217, v46
	v_fma_f32 v48, v46, s2, -v48
	v_fmac_f32_e32 v48, 0x3377d1cf, v46
	v_fmac_f32_e32 v48, 0x3f317217, v46
	v_cmp_lt_f32_e64 s[6:7], |v46|, s12
	s_nop 1
	v_cndmask_b32_e64 v46, v46, v48, s[6:7]
	v_cndmask_b32_e32 v48, 0, v232, vcc
	v_sub_f32_e32 v46, v46, v48
	ds_read_b128 v[48:51], v38 offset:576
	ds_read_b128 v[52:55], v38 offset:592
	v_sub_f32_e32 v46, v47, v46
	v_fmamk_f32 v46, v46, 0x3d800000, v45
	s_waitcnt lgkmcnt(1)
	v_mov_b32_e32 v56, v48
	s_waitcnt lgkmcnt(0)
	v_mov_b32_e32 v57, v52
	v_mov_b32_e32 v52, v49
	v_pk_mul_f32 v[48:49], v[8:9], v[52:53]
	v_mov_b32_e32 v52, v50
	v_pk_fma_f32 v[48:49], v[6:7], v[56:57], v[48:49]
	v_mov_b32_e32 v53, v54
	v_pk_fma_f32 v[48:49], v[12:13], v[52:53], v[48:49]
	v_mov_b32_e32 v54, v51
	v_pk_fma_f32 v[48:49], v[10:11], v[54:55], v[48:49]
	s_nop 0
	v_add_f32_e32 v47, v22, v48
	v_add_f32_e32 v47, v47, v49
	ds_read_b128 v[48:51], v38 offset:608
	ds_read_b128 v[52:55], v38 offset:624
	s_waitcnt lgkmcnt(1)
	v_mov_b32_e32 v56, v48
	s_waitcnt lgkmcnt(0)
	v_mov_b32_e32 v57, v52
	v_mov_b32_e32 v52, v49
	v_pk_mul_f32 v[48:49], v[4:5], v[52:53]
	v_mov_b32_e32 v52, v50
	v_pk_fma_f32 v[48:49], v[2:3], v[56:57], v[48:49]
	v_mov_b32_e32 v53, v54
	v_pk_fma_f32 v[48:49], v[16:17], v[52:53], v[48:49]
	v_mov_b32_e32 v54, v51
	v_pk_fma_f32 v[48:49], v[14:15], v[54:55], v[48:49]
	s_nop 0
	v_add_f32_e32 v47, v47, v48
	v_add_f32_e32 v47, v47, v49
	v_min_f32_e32 v48, 0, v47
	v_mul_f32_e64 v47, |v47|, s5
	v_exp_f32_e32 v47, v47
	s_nop 0
	v_add_f32_e32 v47, 1.0, v47
	v_cmp_gt_f32_e32 vcc, s37, v47
	s_nop 1
	v_cndmask_b32_e64 v49, 0, 32, vcc
	v_ldexp_f32 v47, v47, v49
	v_log_f32_e32 v47, v47
	s_nop 0
	v_mul_f32_e32 v49, 0x3f317217, v47
	v_fma_f32 v49, v47, s2, -v49
	v_fmac_f32_e32 v49, 0x3377d1cf, v47
	v_fmac_f32_e32 v49, 0x3f317217, v47
	v_cmp_lt_f32_e64 s[6:7], |v47|, s12
	s_nop 1
	v_cndmask_b32_e64 v47, v47, v49, s[6:7]
	v_cndmask_b32_e32 v49, 0, v232, vcc
	v_sub_f32_e32 v47, v47, v49
	v_sub_f32_e32 v47, v48, v47
	ds_read_b128 v[48:51], v38 offset:640
	ds_read_b128 v[52:55], v38 offset:656
	v_fmamk_f32 v47, v47, 0x3d800000, v46
	s_waitcnt lgkmcnt(1)
	v_mov_b32_e32 v56, v48
	s_waitcnt lgkmcnt(0)
	v_mov_b32_e32 v57, v52
	v_mov_b32_e32 v52, v49
	v_pk_mul_f32 v[48:49], v[8:9], v[52:53]
	v_mov_b32_e32 v52, v50
	v_pk_fma_f32 v[48:49], v[6:7], v[56:57], v[48:49]
	v_mov_b32_e32 v53, v54
	v_pk_fma_f32 v[48:49], v[12:13], v[52:53], v[48:49]
	v_mov_b32_e32 v54, v51
	v_pk_fma_f32 v[48:49], v[10:11], v[54:55], v[48:49]
	s_nop 0
	v_add_f32_e32 v48, v22, v48
	v_add_f32_e32 v58, v48, v49
	ds_read_b128 v[48:51], v38 offset:672
	ds_read_b128 v[52:55], v38 offset:688
	s_waitcnt lgkmcnt(1)
	v_mov_b32_e32 v56, v48
	s_waitcnt lgkmcnt(0)
	v_mov_b32_e32 v57, v52
	v_mov_b32_e32 v52, v49
	v_pk_mul_f32 v[48:49], v[4:5], v[52:53]
	v_mov_b32_e32 v52, v50
	v_pk_fma_f32 v[48:49], v[2:3], v[56:57], v[48:49]
	v_mov_b32_e32 v53, v54
	v_pk_fma_f32 v[48:49], v[16:17], v[52:53], v[48:49]
	v_mov_b32_e32 v54, v51
	v_pk_fma_f32 v[48:49], v[14:15], v[54:55], v[48:49]
	s_nop 0
	v_add_f32_e32 v48, v58, v48
	v_add_f32_e32 v48, v48, v49
	v_min_f32_e32 v49, 0, v48
	v_mul_f32_e64 v48, |v48|, s5
	v_exp_f32_e32 v48, v48
	s_nop 0
	v_add_f32_e32 v48, 1.0, v48
	v_cmp_gt_f32_e32 vcc, s37, v48
	s_nop 1
	v_cndmask_b32_e64 v50, 0, 32, vcc
	v_ldexp_f32 v48, v48, v50
	v_log_f32_e32 v48, v48
	s_nop 0
	v_mul_f32_e32 v50, 0x3f317217, v48
	v_fma_f32 v50, v48, s2, -v50
	v_fmac_f32_e32 v50, 0x3377d1cf, v48
	v_fmac_f32_e32 v50, 0x3f317217, v48
	v_cmp_lt_f32_e64 s[6:7], |v48|, s12
	s_nop 1
	v_cndmask_b32_e64 v48, v48, v50, s[6:7]
	v_cndmask_b32_e32 v50, 0, v232, vcc
	v_sub_f32_e32 v48, v48, v50
	ds_read_b128 v[50:53], v38 offset:704
	ds_read_b128 v[54:57], v38 offset:720
	v_sub_f32_e32 v48, v49, v48
	v_fmamk_f32 v48, v48, 0x3d800000, v47
	s_waitcnt lgkmcnt(1)
	v_mov_b32_e32 v58, v50
	s_waitcnt lgkmcnt(0)
	v_mov_b32_e32 v59, v54
	v_mov_b32_e32 v54, v51
	v_pk_mul_f32 v[50:51], v[8:9], v[54:55]
	v_mov_b32_e32 v54, v52
	v_pk_fma_f32 v[50:51], v[6:7], v[58:59], v[50:51]
	v_mov_b32_e32 v55, v56
	v_pk_fma_f32 v[50:51], v[12:13], v[54:55], v[50:51]
	v_mov_b32_e32 v56, v53
	v_pk_fma_f32 v[50:51], v[10:11], v[56:57], v[50:51]
	s_nop 0
	v_add_f32_e32 v49, v22, v50
	v_add_f32_e32 v49, v49, v51
	ds_read_b128 v[50:53], v38 offset:736
	ds_read_b128 v[54:57], v38 offset:752
	s_waitcnt lgkmcnt(1)
	v_mov_b32_e32 v58, v50
	s_waitcnt lgkmcnt(0)
	v_mov_b32_e32 v59, v54
	v_mov_b32_e32 v54, v51
	v_pk_mul_f32 v[50:51], v[4:5], v[54:55]
	v_mov_b32_e32 v54, v52
	v_pk_fma_f32 v[50:51], v[2:3], v[58:59], v[50:51]
	v_mov_b32_e32 v55, v56
	v_pk_fma_f32 v[50:51], v[16:17], v[54:55], v[50:51]
	v_mov_b32_e32 v56, v53
	v_pk_fma_f32 v[50:51], v[14:15], v[56:57], v[50:51]
	s_nop 0
	v_add_f32_e32 v49, v49, v50
	v_add_f32_e32 v49, v49, v51
	v_min_f32_e32 v50, 0, v49
	v_mul_f32_e64 v49, |v49|, s5
	v_exp_f32_e32 v49, v49
	s_nop 0
	v_add_f32_e32 v49, 1.0, v49
	v_cmp_gt_f32_e32 vcc, s37, v49
	s_nop 1
	v_cndmask_b32_e64 v51, 0, 32, vcc
	v_ldexp_f32 v49, v49, v51
	v_log_f32_e32 v49, v49
	s_nop 0
	v_mul_f32_e32 v51, 0x3f317217, v49
	v_fma_f32 v51, v49, s2, -v51
	v_fmac_f32_e32 v51, 0x3377d1cf, v49
	v_fmac_f32_e32 v51, 0x3f317217, v49
	v_cmp_lt_f32_e64 s[6:7], |v49|, s12
	s_nop 1
	v_cndmask_b32_e64 v49, v49, v51, s[6:7]
	v_cndmask_b32_e32 v51, 0, v232, vcc
	v_sub_f32_e32 v49, v49, v51
	v_sub_f32_e32 v49, v50, v49
	ds_read_b128 v[50:53], v38 offset:768
	ds_read_b128 v[54:57], v38 offset:784
	v_fmamk_f32 v49, v49, 0x3d800000, v48
	s_waitcnt lgkmcnt(1)
	v_mov_b32_e32 v58, v50
	s_waitcnt lgkmcnt(0)
	v_mov_b32_e32 v59, v54
	v_mov_b32_e32 v54, v51
	v_pk_mul_f32 v[50:51], v[8:9], v[54:55]
	v_mov_b32_e32 v54, v52
	v_pk_fma_f32 v[50:51], v[6:7], v[58:59], v[50:51]
	v_mov_b32_e32 v55, v56
	v_pk_fma_f32 v[50:51], v[12:13], v[54:55], v[50:51]
	v_mov_b32_e32 v56, v53
	v_pk_fma_f32 v[50:51], v[10:11], v[56:57], v[50:51]
	s_nop 0
	v_add_f32_e32 v50, v22, v50
	v_add_f32_e32 v60, v50, v51
	ds_read_b128 v[50:53], v38 offset:800
	ds_read_b128 v[54:57], v38 offset:816
	s_waitcnt lgkmcnt(1)
	v_mov_b32_e32 v58, v50
	s_waitcnt lgkmcnt(0)
	v_mov_b32_e32 v59, v54
	v_mov_b32_e32 v54, v51
	v_pk_mul_f32 v[50:51], v[4:5], v[54:55]
	v_mov_b32_e32 v54, v52
	v_pk_fma_f32 v[50:51], v[2:3], v[58:59], v[50:51]
	v_mov_b32_e32 v55, v56
	v_pk_fma_f32 v[50:51], v[16:17], v[54:55], v[50:51]
	v_mov_b32_e32 v56, v53
	v_pk_fma_f32 v[50:51], v[14:15], v[56:57], v[50:51]
	s_nop 0
	v_add_f32_e32 v50, v60, v50
	v_add_f32_e32 v50, v50, v51
	v_min_f32_e32 v51, 0, v50
	v_mul_f32_e64 v50, |v50|, s5
	v_exp_f32_e32 v50, v50
	s_nop 0
	v_add_f32_e32 v50, 1.0, v50
	v_cmp_gt_f32_e32 vcc, s37, v50
	s_nop 1
	v_cndmask_b32_e64 v52, 0, 32, vcc
	v_ldexp_f32 v50, v50, v52
	v_log_f32_e32 v50, v50
	s_nop 0
	v_mul_f32_e32 v52, 0x3f317217, v50
	v_fma_f32 v52, v50, s2, -v52
	v_fmac_f32_e32 v52, 0x3377d1cf, v50
	v_fmac_f32_e32 v52, 0x3f317217, v50
	v_cmp_lt_f32_e64 s[6:7], |v50|, s12
	s_nop 1
	v_cndmask_b32_e64 v50, v50, v52, s[6:7]
	v_cndmask_b32_e32 v52, 0, v232, vcc
	v_sub_f32_e32 v50, v50, v52
	ds_read_b128 v[52:55], v38 offset:832
	ds_read_b128 v[56:59], v38 offset:848
	v_sub_f32_e32 v50, v51, v50
	v_fmamk_f32 v50, v50, 0x3d800000, v49
	s_waitcnt lgkmcnt(1)
	v_mov_b32_e32 v60, v52
	s_waitcnt lgkmcnt(0)
	v_mov_b32_e32 v61, v56
	v_mov_b32_e32 v56, v53
	v_pk_mul_f32 v[52:53], v[8:9], v[56:57]
	v_mov_b32_e32 v56, v54
	v_pk_fma_f32 v[52:53], v[6:7], v[60:61], v[52:53]
	v_mov_b32_e32 v57, v58
	v_pk_fma_f32 v[52:53], v[12:13], v[56:57], v[52:53]
	v_mov_b32_e32 v58, v55
	v_pk_fma_f32 v[52:53], v[10:11], v[58:59], v[52:53]
	s_nop 0
	v_add_f32_e32 v51, v22, v52
	v_add_f32_e32 v51, v51, v53
	ds_read_b128 v[52:55], v38 offset:864
	ds_read_b128 v[56:59], v38 offset:880
	s_waitcnt lgkmcnt(1)
	v_mov_b32_e32 v60, v52
	s_waitcnt lgkmcnt(0)
	v_mov_b32_e32 v61, v56
	v_mov_b32_e32 v56, v53
	v_pk_mul_f32 v[52:53], v[4:5], v[56:57]
	v_mov_b32_e32 v56, v54
	v_pk_fma_f32 v[52:53], v[2:3], v[60:61], v[52:53]
	v_mov_b32_e32 v57, v58
	v_pk_fma_f32 v[52:53], v[16:17], v[56:57], v[52:53]
	v_mov_b32_e32 v58, v55
	v_pk_fma_f32 v[52:53], v[14:15], v[58:59], v[52:53]
	s_nop 0
	v_add_f32_e32 v51, v51, v52
	v_add_f32_e32 v51, v51, v53
	v_min_f32_e32 v52, 0, v51
	v_mul_f32_e64 v51, |v51|, s5
	v_exp_f32_e32 v51, v51
	s_nop 0
	v_add_f32_e32 v51, 1.0, v51
	v_cmp_gt_f32_e32 vcc, s37, v51
	s_nop 1
	v_cndmask_b32_e64 v53, 0, 32, vcc
	v_ldexp_f32 v51, v51, v53
	v_log_f32_e32 v51, v51
	s_nop 0
	v_mul_f32_e32 v53, 0x3f317217, v51
	v_fma_f32 v53, v51, s2, -v53
	v_fmac_f32_e32 v53, 0x3377d1cf, v51
	v_fmac_f32_e32 v53, 0x3f317217, v51
	v_cmp_lt_f32_e64 s[6:7], |v51|, s12
	s_nop 1
	v_cndmask_b32_e64 v51, v51, v53, s[6:7]
	v_cndmask_b32_e32 v53, 0, v232, vcc
	v_sub_f32_e32 v51, v51, v53
	v_sub_f32_e32 v51, v52, v51
	ds_read_b128 v[52:55], v38 offset:896
	ds_read_b128 v[56:59], v38 offset:912
	v_fmamk_f32 v51, v51, 0x3d800000, v50
	s_waitcnt lgkmcnt(1)
	v_mov_b32_e32 v60, v52
	s_waitcnt lgkmcnt(0)
	v_mov_b32_e32 v61, v56
	v_mov_b32_e32 v56, v53
	v_pk_mul_f32 v[52:53], v[8:9], v[56:57]
	v_mov_b32_e32 v56, v54
	v_pk_fma_f32 v[52:53], v[6:7], v[60:61], v[52:53]
	v_mov_b32_e32 v57, v58
	v_pk_fma_f32 v[52:53], v[12:13], v[56:57], v[52:53]
	v_mov_b32_e32 v58, v55
	v_pk_fma_f32 v[52:53], v[10:11], v[58:59], v[52:53]
	s_nop 0
	v_add_f32_e32 v52, v22, v52
	v_add_f32_e32 v62, v52, v53
	ds_read_b128 v[52:55], v38 offset:928
	ds_read_b128 v[56:59], v38 offset:944
	s_waitcnt lgkmcnt(1)
	v_mov_b32_e32 v60, v52
	s_waitcnt lgkmcnt(0)
	v_mov_b32_e32 v61, v56
	v_mov_b32_e32 v56, v53
	v_pk_mul_f32 v[52:53], v[4:5], v[56:57]
	v_mov_b32_e32 v56, v54
	v_pk_fma_f32 v[52:53], v[2:3], v[60:61], v[52:53]
	v_mov_b32_e32 v57, v58
	v_pk_fma_f32 v[52:53], v[16:17], v[56:57], v[52:53]
	v_mov_b32_e32 v58, v55
	v_pk_fma_f32 v[52:53], v[14:15], v[58:59], v[52:53]
	s_nop 0
	v_add_f32_e32 v52, v62, v52
	v_add_f32_e32 v52, v52, v53
	v_min_f32_e32 v53, 0, v52
	v_mul_f32_e64 v52, |v52|, s5
	v_exp_f32_e32 v52, v52
	s_nop 0
	v_add_f32_e32 v52, 1.0, v52
	v_cmp_gt_f32_e32 vcc, s37, v52
	s_nop 1
	v_cndmask_b32_e64 v54, 0, 32, vcc
	v_ldexp_f32 v52, v52, v54
	v_log_f32_e32 v52, v52
	s_nop 0
	v_mul_f32_e32 v54, 0x3f317217, v52
	v_fma_f32 v54, v52, s2, -v54
	v_fmac_f32_e32 v54, 0x3377d1cf, v52
	v_fmac_f32_e32 v54, 0x3f317217, v52
	v_cmp_lt_f32_e64 s[6:7], |v52|, s12
	s_nop 1
	v_cndmask_b32_e64 v52, v52, v54, s[6:7]
	v_cndmask_b32_e32 v54, 0, v232, vcc
	v_sub_f32_e32 v52, v52, v54
	v_sub_f32_e32 v52, v53, v52
	v_fmamk_f32 v62, v52, 0x3d800000, v51
	ds_read_b128 v[52:55], v38 offset:960
	ds_read_b128 v[56:59], v38 offset:976
	s_waitcnt lgkmcnt(1)
	v_mov_b32_e32 v60, v52
	s_waitcnt lgkmcnt(0)
	v_mov_b32_e32 v61, v56
	v_mov_b32_e32 v56, v53
	v_pk_mul_f32 v[8:9], v[8:9], v[56:57]
	s_nop 0
	v_pk_fma_f32 v[6:7], v[6:7], v[60:61], v[8:9]
	v_mov_b32_e32 v8, v54
	v_mov_b32_e32 v9, v58
	v_pk_fma_f32 v[6:7], v[12:13], v[8:9], v[6:7]
	v_mov_b32_e32 v58, v55
	v_pk_fma_f32 v[6:7], v[10:11], v[58:59], v[6:7]
	s_nop 0
	v_add_f32_e32 v6, v22, v6
	v_add_f32_e32 v22, v6, v7
	ds_read_b128 v[6:9], v38 offset:992
	ds_read_b128 v[10:13], v38 offset:1008
	s_waitcnt lgkmcnt(1)
	v_mov_b32_e32 v52, v6
	s_waitcnt lgkmcnt(0)
	v_mov_b32_e32 v53, v10
	v_mov_b32_e32 v10, v7
	v_pk_mul_f32 v[4:5], v[4:5], v[10:11]
	s_nop 0
	v_pk_fma_f32 v[2:3], v[2:3], v[52:53], v[4:5]
	v_mov_b32_e32 v4, v8
	v_mov_b32_e32 v5, v12
	v_pk_fma_f32 v[2:3], v[16:17], v[4:5], v[2:3]
	v_mov_b32_e32 v12, v9
	v_pk_fma_f32 v[2:3], v[14:15], v[12:13], v[2:3]
	v_lshlrev_b32_e32 v13, 16, v23
	v_add_f32_e32 v2, v22, v2
	v_add_f32_e32 v2, v2, v3
	v_min_f32_e32 v3, 0, v2
	v_mul_f32_e64 v2, |v2|, s5
	v_exp_f32_e32 v2, v2
	v_lshlrev_b32_e32 v23, 16, v30
	v_lshlrev_b32_e32 v12, 16, v24
	v_lshlrev_b32_e32 v24, 16, v31
	v_add_f32_e32 v2, 1.0, v2
	v_cmp_gt_f32_e32 vcc, s37, v2
	v_lshlrev_b32_e32 v15, 16, v26
	v_lshlrev_b32_e32 v14, 16, v25
	v_cndmask_b32_e64 v4, 0, 32, vcc
	v_ldexp_f32 v2, v2, v4
	v_log_f32_e32 v2, v2
	v_lshlrev_b32_e32 v17, 16, v28
	v_lshlrev_b32_e32 v16, 16, v27
	v_lshlrev_b32_e32 v22, 16, v29
	v_mul_f32_e32 v4, 0x3f317217, v2
	v_fma_f32 v4, v2, s2, -v4
	v_fmac_f32_e32 v4, 0x3377d1cf, v2
	v_fmac_f32_e32 v4, 0x3f317217, v2
	v_cmp_lt_f32_e64 s[6:7], |v2|, s12
	v_lshlrev_b32_e32 v25, 16, v32
	v_lshlrev_b32_e32 v27, 16, v34
	v_cndmask_b32_e64 v2, v2, v4, s[6:7]
	v_cndmask_b32_e32 v4, 0, v232, vcc
	v_sub_f32_e32 v2, v2, v4
	v_sub_f32_e32 v2, v3, v2
	v_fmamk_f32 v3, v2, 0x3d800000, v62
	v_lshl_add_u32 v2, v18, 2, 0
	ds_write_b32 v2, v3 offset:4096
	v_add_u32_e32 v2, 0, v208
	s_waitcnt lgkmcnt(0)
	s_barrier
	ds_read2st64_b32 v[4:5], v2 offset0:16 offset1:18
	ds_read2st64_b32 v[6:7], v2 offset0:20 offset1:22
	v_cmp_lt_i32_e64 s[6:7], 1, v1
	v_cmp_lt_i32_e32 vcc, 0, v1
	v_lshlrev_b32_e32 v26, 16, v33
	s_waitcnt lgkmcnt(1)
	v_cndmask_b32_e64 v8, 0, v5, s[6:7]
	v_cmp_lt_i32_e64 s[6:7], 2, v1
	v_add_f32_e32 v30, 0, v4
	s_waitcnt lgkmcnt(0)
	v_mov_b32_e32 v10, v6
	v_cndmask_b32_e64 v9, 0, v6, s[6:7]
	v_cmp_lt_i32_e64 s[6:7], 3, v1
	v_cndmask_b32_e32 v1, 0, v30, vcc
	v_add_f32_e32 v31, v1, v8
	v_mov_b32_e32 v8, v5
	v_cndmask_b32_e64 v11, 0, v7, s[6:7]
	v_pk_add_f32 v[4:5], v[30:31], v[8:9]
	v_mov_b32_e32 v2, v7
	v_pk_add_f32 v[10:11], v[4:5], v[10:11]
	v_lshlrev_b32_e32 v29, 16, v36
	v_add_f32_e32 v1, v37, v11
	v_pk_add_f32 v[2:3], v[10:11], v[2:3]
	v_lshlrev_b32_e32 v28, 16, v35
	v_sub_f32_e32 v1, v2, v1
	v_mul_f32_e32 v1, 0x3fb8aa3b, v1
	v_exp_f32_e32 v4, v1
	v_add_f32_e32 v1, v39, v11
	v_sub_f32_e32 v1, v2, v1
	v_mul_f32_e32 v1, 0x3fb8aa3b, v1
	v_exp_f32_e32 v5, v1
	v_add_f32_e32 v1, v40, v11
	v_sub_f32_e32 v1, v2, v1
	v_mul_f32_e32 v1, 0x3fb8aa3b, v1
	v_exp_f32_e32 v6, v1
	v_add_f32_e32 v1, v41, v11
	v_sub_f32_e32 v1, v2, v1
	v_mul_f32_e32 v1, 0x3fb8aa3b, v1
	v_exp_f32_e32 v7, v1
	v_add_f32_e32 v1, v42, v11
	v_sub_f32_e32 v1, v2, v1
	v_pk_mul_f32 v[4:5], v[4:5], v[12:13]
	v_pk_mul_f32 v[6:7], v[6:7], v[14:15]
	v_mul_f32_e32 v1, 0x3fb8aa3b, v1
	v_cvt_pk_bf16_f32 v4, v4, v5
	v_cvt_pk_bf16_f32 v5, v6, v7
	v_exp_f32_e32 v6, v1
	v_add_f32_e32 v1, v43, v11
	v_sub_f32_e32 v1, v2, v1
	v_mul_f32_e32 v1, 0x3fb8aa3b, v1
	v_exp_f32_e32 v7, v1
	v_add_f32_e32 v1, v44, v11
	v_sub_f32_e32 v1, v2, v1
	v_mul_f32_e32 v1, 0x3fb8aa3b, v1
	v_exp_f32_e32 v8, v1
	v_add_f32_e32 v1, v45, v11
	v_sub_f32_e32 v1, v2, v1
	v_mul_f32_e32 v1, 0x3fb8aa3b, v1
	v_exp_f32_e32 v9, v1
	v_add_f32_e32 v1, v46, v11
	v_sub_f32_e32 v1, v2, v1
	v_pk_mul_f32 v[6:7], v[6:7], v[16:17]
	v_pk_mul_f32 v[8:9], v[8:9], v[22:23]
	v_mul_f32_e32 v1, 0x3fb8aa3b, v1
	v_cvt_pk_bf16_f32 v6, v6, v7
	v_cvt_pk_bf16_f32 v7, v8, v9
	v_exp_f32_e32 v8, v1
	v_add_f32_e32 v1, v47, v11
	v_sub_f32_e32 v1, v2, v1
	v_mul_f32_e32 v1, 0x3fb8aa3b, v1
	v_exp_f32_e32 v9, v1
	v_add_f32_e32 v1, v48, v11
	v_sub_f32_e32 v1, v2, v1
	v_mul_f32_e32 v1, 0x3fb8aa3b, v1
	v_exp_f32_e32 v12, v1
	v_add_f32_e32 v1, v49, v11
	v_sub_f32_e32 v1, v2, v1
	v_mul_f32_e32 v1, 0x3fb8aa3b, v1
	v_exp_f32_e32 v13, v1
	v_add_f32_e32 v1, v50, v11
	v_sub_f32_e32 v1, v2, v1
	v_pk_mul_f32 v[8:9], v[8:9], v[24:25]
	v_pk_mul_f32 v[12:13], v[12:13], v[26:27]
	v_mul_f32_e32 v1, 0x3fb8aa3b, v1
	v_cvt_pk_bf16_f32 v8, v8, v9
	v_cvt_pk_bf16_f32 v9, v12, v13
	v_exp_f32_e32 v12, v1
	v_add_f32_e32 v1, v51, v11
	v_sub_f32_e32 v1, v2, v1
	v_mul_f32_e32 v1, 0x3fb8aa3b, v1
	v_exp_f32_e32 v13, v1
	v_add_f32_e32 v1, v11, v62
	v_sub_f32_e32 v1, v2, v1
	v_mul_f32_e32 v1, 0x3fb8aa3b, v1
	v_pk_mul_f32 v[12:13], v[12:13], v[28:29]
	v_lshlrev_b32_e32 v15, 16, v21
	v_cvt_pk_bf16_f32 v10, v12, v13
	v_exp_f32_e32 v12, v1
	v_sub_f32_e32 v1, v2, v3
	v_mul_f32_e32 v1, 0x3fb8aa3b, v1
	v_exp_f32_e32 v13, v1
	v_lshlrev_b32_e32 v14, 16, v20
	v_ashrrev_i32_e32 v1, 31, v0
	v_cmp_gt_u32_e32 vcc, s4, v18
	v_pk_mul_f32 v[12:13], v[12:13], v[14:15]
	s_nop 0
	v_cvt_pk_bf16_f32 v11, v12, v13
	v_lshlrev_b32_e32 v12, 7, v19
	v_mov_b32_e32 v13, v209
	v_lshl_add_u64 v[0:1], v[0:1], 1, v[12:13]
	v_lshl_add_u64 v[0:1], s[50:51], 0, v[0:1]
	v_lshl_add_u64 v[0:1], v[0:1], 0, s[94:95]
	global_store_dwordx4 v[0:1], v[4:7], off offset:-16
	global_store_dwordx4 v[0:1], v[8:11], off
	s_and_saveexec_b64 s[6:7], vcc
	s_cbranch_execz .LBB0_984
	v_mul_f32_e32 v0, 0x3fb8aa3b, v2
	v_exp_f32_e32 v2, v0
	v_lshl_add_u64 v[0:1], s[50:51], 0, v[208:209]
	v_lshl_add_u64 v[0:1], v[0:1], 0, s[90:91]
	global_store_dword v[0:1], v2, off
	s_branch .LBB0_984
